# phase 0: removed store-drain waits at W1 tile loop top and inside the wg fill loads
# speedup vs baseline: 1.0003x; 1.0003x over previous
; __device__ void wt_tile(const float* src, int ld, int k0, int n0, bf16_t* dst, int Kdst, const float* kscale, float mul, LAS float* tile, bool rotperm = false, int drow0 = -1) {
;     ...
;     for (int i = 0; i < 16; ++i) { const int k = (tid >> 7) + 4 * i, n = tid & 127; v[i] = src[(size_t)(k0 + k) * ld + n0 + n]; }
; #pragma unroll
;     for (int i = 0; i < 16; ++i) { const int k = (tid >> 7) + 4 * i, n = tid & 127; float x = v[i] * mul; if (kscale) x *= kscale[k0 + k]; tile[k * 129 + n] = x; }
;     __syncthreads();
.LBB0_1041:
	s_ashr_i32 s3, s7, 4
	s_and_b32 s8, s5, 0x3c0
	s_lshl_b32 s2, s3, 7
	v_mov_b32_e32 v0, v162
	s_cmp_lt_i32 s3, 4
	s_cselect_b64 vcc, -1, 0
	s_waitcnt lgkmcnt(0)
	v_lshlrev_b32_e32 v3, 2, v0
	v_ashrrev_i32_e32 v4, 5, v0
	v_lshlrev_b32_e32 v5, 1, v0
	s_cmp_lt_i32 s3, 8
	v_ashrrev_i32_e32 v2, 7, v0
	v_cndmask_b32_e32 v19, 1.0, v218, vcc
	v_and_b32_e32 v0, 0x1fc, v3
	v_and_b32_e32 v44, 62, v5
	v_lshlrev_b32_e32 v3, 2, v4
	v_add_u32_e32 v5, s2, v4
	v_lshlrev_b32_e32 v6, 1, v4
	v_bfe_u32 v8, v4, 6, 1
	v_add_u32_e32 v9, 16, v4
	v_add_u32_e32 v10, 32, v4
	v_add_u32_e32 v11, 48, v4
	v_add_u32_e32 v12, 64, v4
	v_add_u32_e32 v13, 0x50, v4
	v_add_u32_e32 v14, 0x60, v4
	v_add_u32_e32 v4, 0x70, v4
	s_cselect_b64 vcc, -1, 0
	s_ashr_i32 s3, s2, 31
	v_add_u32_e32 v7, s8, v2
	v_mul_lo_u32 v2, v2, s9
	v_add_u32_e32 v21, s2, v9
	v_add_u32_e32 v25, s2, v10
	v_add_u32_e32 v29, s2, v11
	v_add_u32_e32 v47, s2, v12
	v_add_u32_e32 v48, s2, v13
	v_add_u32_e32 v49, s2, v14
	v_add_u32_e32 v50, s2, v4
	s_lshl_b64 s[2:3], s[2:3], 2
	v_add3_u32 v46, 0, v0, v2
	v_mul_u32_u24_e32 v2, 0x204, v44
	v_and_b32_e32 v17, 0xffffff80, v5
	v_and_b32_e32 v6, 0x7e, v6
	v_lshlrev_b32_e32 v23, 1, v9
	v_lshlrev_b32_e32 v27, 1, v10
	v_lshlrev_b32_e32 v31, 1, v11
	s_add_u32 s2, s14, s2
	v_bfe_u32 v9, v9, 6, 1
	v_bfe_u32 v10, v10, 6, 1
	v_bfe_u32 v11, v11, 6, 1
	v_lshlrev_b32_e32 v33, 1, v12
	v_lshlrev_b32_e32 v35, 1, v13
	v_or3_b32 v6, v8, v17, v6
	v_add3_u32 v51, 0, v2, v3
	v_and_b32_e32 v3, 0xffffff80, v21
	v_and_b32_e32 v8, 0x7e, v23
	v_and_b32_e32 v17, 0xffffff80, v25
	v_and_b32_e32 v23, 0x7e, v27
	v_and_b32_e32 v27, 0xffffff80, v29
	v_and_b32_e32 v31, 0x7e, v31
	s_addc_u32 s3, s15, s3
	v_add_u32_e32 v22, 16, v7
	v_add_u32_e32 v24, 20, v7
	v_add_u32_e32 v26, 24, v7
	v_add_u32_e32 v28, 28, v7
	v_add_u32_e32 v30, 32, v7
	v_add_u32_e32 v32, 36, v7
	v_bfe_u32 v12, v12, 6, 1
	v_bfe_u32 v13, v13, 6, 1
	v_lshlrev_b32_e32 v37, 1, v14
	v_lshlrev_b32_e32 v39, 1, v4
	v_and_b32_e32 v41, 0xffffff80, v47
	v_and_b32_e32 v33, 0x7e, v33
	v_and_b32_e32 v43, 0xffffff80, v48
	v_and_b32_e32 v35, 0x7e, v35
	v_cndmask_b32_e32 v2, v5, v6, vcc
	v_or3_b32 v5, v9, v3, v8
	v_or3_b32 v6, v10, v17, v23
	v_or3_b32 v8, v11, v27, v31
	v_lshl_add_u64 v[10:11], s[2:3], 0, v[0:1]
	v_add_u32_e32 v15, 4, v7
	v_add_u32_e32 v16, 8, v7
	v_add_u32_e32 v20, 12, v7
	v_add_u32_e32 v34, 40, v7
	v_add_u32_e32 v36, 44, v7
	v_add_u32_e32 v38, 48, v7
	v_add_u32_e32 v40, 52, v7
	v_add_u32_e32 v42, 56, v7
	v_add_u32_e32 v45, 60, v7
	v_bfe_u32 v14, v14, 6, 1
	v_bfe_u32 v4, v4, 6, 1
	v_and_b32_e32 v52, 0xffffff80, v49
	v_and_b32_e32 v37, 0x7e, v37
	v_and_b32_e32 v53, 0xffffff80, v50
	v_and_b32_e32 v39, 0x7e, v39
	v_or3_b32 v9, v12, v41, v33
	v_or3_b32 v54, v13, v43, v35
	v_cndmask_b32_e32 v6, v25, v6, vcc
	v_cndmask_b32_e32 v8, v29, v8, vcc
	v_mad_i64_i32 v[12:13], s[2:3], v7, s10, v[10:11]
	v_mad_i64_i32 v[22:23], s[2:3], v22, s10, v[10:11]
	v_mad_i64_i32 v[24:25], s[2:3], v24, s10, v[10:11]
	v_mad_i64_i32 v[26:27], s[2:3], v26, s10, v[10:11]
	v_mad_i64_i32 v[28:29], s[2:3], v28, s10, v[10:11]
	v_mad_i64_i32 v[30:31], s[2:3], v30, s10, v[10:11]
	v_mad_i64_i32 v[32:33], s[2:3], v32, s10, v[10:11]
	v_or3_b32 v52, v14, v52, v37
	v_or3_b32 v53, v4, v53, v39
	v_cndmask_b32_e32 v4, v21, v5, vcc
	v_mad_i64_i32 v[14:15], s[2:3], v15, s10, v[10:11]
	v_mad_i64_i32 v[16:17], s[2:3], v16, s10, v[10:11]
	v_mad_i64_i32 v[20:21], s[2:3], v20, s10, v[10:11]
	v_mad_i64_i32 v[34:35], s[2:3], v34, s10, v[10:11]
	v_mad_i64_i32 v[36:37], s[2:3], v36, s10, v[10:11]
	v_mad_i64_i32 v[38:39], s[2:3], v38, s10, v[10:11]
	v_mad_i64_i32 v[40:41], s[2:3], v40, s10, v[10:11]
	v_mad_i64_i32 v[42:43], s[2:3], v42, s10, v[10:11]
	v_mad_i64_i32 v[10:11], s[2:3], v45, s10, v[10:11]
	global_load_dword v45, v[12:13], off
	global_load_dword v55, v[14:15], off
	global_load_dword v56, v[16:17], off
	global_load_dword v57, v[20:21], off
	s_nop 0
	global_load_dword v22, v[22:23], off
	s_nop 0
	global_load_dword v23, v[24:25], off
	s_nop 0
	global_load_dword v24, v[26:27], off
	global_load_dword v25, v[28:29], off
	s_nop 0
	global_load_dword v26, v[30:31], off
	global_load_dword v27, v[32:33], off
	global_load_dword v28, v[34:35], off
	global_load_dword v29, v[36:37], off
	s_nop 0
	global_load_dword v30, v[38:39], off
	global_load_dword v31, v[40:41], off
	global_load_dword v32, v[42:43], off
	global_load_dword v33, v[10:11], off
	s_lshl_b32 s2, s8, 1
	v_cndmask_b32_e32 v10, v47, v9, vcc
	v_cndmask_b32_e32 v12, v48, v54, vcc
	v_cndmask_b32_e32 v14, v49, v52, vcc
	v_cndmask_b32_e32 v16, v50, v53, vcc
	s_add_u32 s2, s0, s2
	v_ashrrev_i32_e32 v3, 31, v2
	v_ashrrev_i32_e32 v5, 31, v4
	v_ashrrev_i32_e32 v7, 31, v6
	v_ashrrev_i32_e32 v9, 31, v8
	v_ashrrev_i32_e32 v11, 31, v10
	v_ashrrev_i32_e32 v13, 31, v12
	v_ashrrev_i32_e32 v15, 31, v14
	v_ashrrev_i32_e32 v17, 31, v16
	v_lshlrev_b32_e32 v0, 1, v44
	s_addc_u32 s3, s4, 0
	v_lshlrev_b64 v[2:3], 11, v[2:3]
	v_lshlrev_b64 v[4:5], 11, v[4:5]
	v_lshlrev_b64 v[6:7], 11, v[6:7]
	v_lshlrev_b64 v[8:9], 11, v[8:9]
	v_lshlrev_b64 v[10:11], 11, v[10:11]
	v_lshlrev_b64 v[12:13], 11, v[12:13]
	v_lshlrev_b64 v[14:15], 11, v[14:15]
	v_lshlrev_b64 v[16:17], 11, v[16:17]
	v_lshl_add_u64 v[20:21], s[2:3], 0, v[0:1]
	v_lshl_add_u64 v[2:3], v[20:21], 0, v[2:3]
	v_lshl_add_u64 v[4:5], v[20:21], 0, v[4:5]
	v_lshl_add_u64 v[6:7], v[20:21], 0, v[6:7]
	v_lshl_add_u64 v[8:9], v[20:21], 0, v[8:9]
	v_lshl_add_u64 v[10:11], v[20:21], 0, v[10:11]
	v_lshl_add_u64 v[12:13], v[20:21], 0, v[12:13]
	v_lshl_add_u64 v[14:15], v[20:21], 0, v[14:15]
	v_lshl_add_u64 v[16:17], v[20:21], 0, v[16:17]
	s_add_i32 s7, s7, s89
	s_add_i32 s5, s5, s6
	s_cmpk_gt_i32 s7, 0x1ff
	s_waitcnt vmcnt(15)
	v_mul_f32_e32 v0, v19, v45
	s_waitcnt vmcnt(14)
	v_mul_f32_e32 v20, v19, v55
	s_waitcnt vmcnt(13)
	v_mul_f32_e32 v21, v19, v56
	s_waitcnt vmcnt(12)
	v_mul_f32_e32 v34, v19, v57
	s_waitcnt vmcnt(11)
	v_mul_f32_e32 v22, v19, v22
	s_waitcnt vmcnt(10)
	v_mul_f32_e32 v23, v19, v23
	s_waitcnt vmcnt(9)
	v_mul_f32_e32 v24, v19, v24
	s_waitcnt vmcnt(8)
	v_mul_f32_e32 v25, v19, v25
	s_waitcnt vmcnt(7)
	v_mul_f32_e32 v26, v19, v26
	s_waitcnt vmcnt(6)
	v_mul_f32_e32 v27, v19, v27
	s_waitcnt vmcnt(5)
	v_mul_f32_e32 v28, v19, v28
	s_waitcnt vmcnt(4)
	v_mul_f32_e32 v29, v19, v29
	s_waitcnt vmcnt(3)
	v_mul_f32_e32 v30, v19, v30
	s_waitcnt vmcnt(2)
	v_mul_f32_e32 v31, v19, v31
	s_waitcnt vmcnt(1)
	v_mul_f32_e32 v32, v19, v32
	s_waitcnt vmcnt(0)
	v_mul_f32_e32 v19, v19, v33
	ds_write_b32 v46, v0
	ds_write_b32 v46, v20 offset:2064
	ds_write_b32 v46, v21 offset:4128
	ds_write_b32 v46, v34 offset:6192
	ds_write_b32 v46, v22 offset:8256
	ds_write_b32 v46, v23 offset:10320
	ds_write_b32 v46, v24 offset:12384
	ds_write_b32 v46, v25 offset:14448
	ds_write_b32 v46, v26 offset:16512
	ds_write_b32 v46, v27 offset:18576
	ds_write_b32 v46, v28 offset:20640
	ds_write_b32 v46, v29 offset:22704
	ds_write_b32 v46, v30 offset:24768
	ds_write_b32 v46, v31 offset:26832
	ds_write_b32 v46, v32 offset:28896
	ds_write_b32 v46, v19 offset:30960
	s_waitcnt lgkmcnt(0)
	s_barrier
; #define LAS __attribute__((address_space(3)))
; __device__ __forceinline__ unsigned cvt_pk_bf16(float lo, float hi) { unsigned r; asm volatile("v_cvt_pk_bf16_f32 %0, %1, %2" : "=v"(r) : "v"(lo), "v"(hi)); return r; }
; __device__ void wt_tile(const float* src, int ld, int k0, int n0, bf16_t* dst, int Kdst, const float* kscale, float mul, LAS float* tile, bool rotperm = false, int drow0 = -1) {
;     ...
;     for (int i = 0; i < 8; ++i) { const int n = (tid >> 5) + 16 * i, k2 = (tid & 31) * 2;
;         const float a = tile[k2 * 129 + n], b = tile[(k2 + 1) * 129 + n]; int nn = (drow0 >= 0 ? drow0 : n0) + n; if (rotperm) nn = (nn & ~127) | (2 * (nn & 63) + ((nn >> 6) & 1));
;         *(unsigned*)(dst + (size_t)nn * Kdst + k0 + k2) = cvt_pk_bf16(a, b); }
;     __syncthreads();
; __device__ void phase0(const Params& P, LAS unsigned char* lds, const int G, const int bid) {
;     ...
;     LAS float* wg = (LAS float*)(lds + 40960);
;     { const float* win = P.in[5];
; #pragma unroll
;       for (int i = 0; i < 8; ++i) { const int k = (tid >> 2) + 128 * i, q = tid & 3; const f32x4 v = *(const f32x4*)(win + (size_t)k * INCOLS + NPROJ + 4 * q);
;           const int slot = (k & 3) * 256 + (k >> 8) * 64 + ((k >> 2) & 63); *(LAS f32x4*)(wg + slot * 20 + 4 * q) = v; }
;       __syncthreads(); }
	ds_read2_b32 v[116:117], v51 offset1:129
	ds_read2_b32 v[118:119], v51 offset0:16 offset1:145
	ds_read2_b32 v[120:121], v51 offset0:32 offset1:161
	ds_read2_b32 v[122:123], v51 offset0:48 offset1:177
	ds_read2_b32 v[124:125], v51 offset0:64 offset1:193
	ds_read2_b32 v[126:127], v51 offset0:80 offset1:209
	ds_read2_b32 v[128:129], v51 offset0:96 offset1:225
	ds_read2_b32 v[130:131], v51 offset0:112 offset1:241
	s_waitcnt lgkmcnt(7)
	v_cvt_pk_bf16_f32 v0, v116, v117
	global_store_dword v[2:3], v0, off
	s_waitcnt lgkmcnt(6)
	v_cvt_pk_bf16_f32 v0, v118, v119
	global_store_dword v[4:5], v0, off
	s_waitcnt lgkmcnt(5)
	v_cvt_pk_bf16_f32 v0, v120, v121
	global_store_dword v[6:7], v0, off
	s_waitcnt lgkmcnt(4)
	v_cvt_pk_bf16_f32 v0, v122, v123
	global_store_dword v[8:9], v0, off
	s_waitcnt lgkmcnt(3)
	v_cvt_pk_bf16_f32 v0, v124, v125
	global_store_dword v[10:11], v0, off
	s_waitcnt lgkmcnt(2)
	v_cvt_pk_bf16_f32 v0, v126, v127
	global_store_dword v[12:13], v0, off
	s_waitcnt lgkmcnt(1)
	v_cvt_pk_bf16_f32 v0, v128, v129
	global_store_dword v[14:15], v0, off
	s_waitcnt lgkmcnt(0)
	v_cvt_pk_bf16_f32 v0, v130, v131
	global_store_dword v[16:17], v0, off
	s_barrier
	s_cbranch_scc0 .LBB0_1041
.LBB0_1042:
	v_ashrrev_i32_e32 v19, 2, v18
	v_lshlrev_b32_e32 v0, 4, v18
	v_mov_b64_e32 v[32:33], s[14:15]
	v_and_b32_e32 v0, 48, v0
	s_waitcnt lgkmcnt(0)
	v_mad_i64_i32 v[2:3], s[2:3], v19, s10, v[32:33]
	v_lshl_add_u64 v[2:3], v[2:3], 0, v[0:1]
	v_add_u32_e32 v38, 0x80, v19
	v_add_co_u32_e32 v2, vcc, 0x4000, v2
	v_mad_i64_i32 v[4:5], s[2:3], v38, s10, v[32:33]
	s_nop 0
	v_addc_co_u32_e32 v3, vcc, 0, v3, vcc
	v_lshl_add_u64 v[4:5], v[4:5], 0, v[0:1]
	s_movk_i32 s14, 0x4000
	v_add_co_u32_e32 v6, vcc, s14, v4
	v_add_u32_e32 v39, 0x100, v19
	s_nop 0
	v_addc_co_u32_e32 v7, vcc, 0, v5, vcc
	global_load_dwordx4 v[2:5], v[2:3], off
	s_nop 0
	global_load_dwordx4 v[6:9], v[6:7], off
	v_mad_i64_i32 v[10:11], s[2:3], v39, s10, v[32:33]
	v_lshl_add_u64 v[10:11], v[10:11], 0, v[0:1]
	v_add_u32_e32 v40, 0x180, v19
	v_add_co_u32_e32 v10, vcc, s14, v10
	v_mad_i64_i32 v[12:13], s[2:3], v40, s10, v[32:33]
	s_nop 0
	v_addc_co_u32_e32 v11, vcc, 0, v11, vcc
	v_lshl_add_u64 v[12:13], v[12:13], 0, v[0:1]
	v_add_co_u32_e32 v14, vcc, s14, v12
	v_add_u32_e32 v41, 0x200, v19
	s_nop 0
	v_addc_co_u32_e32 v15, vcc, 0, v13, vcc
	global_load_dwordx4 v[10:13], v[10:11], off
	s_nop 0
	global_load_dwordx4 v[14:17], v[14:15], off
	v_mad_i64_i32 v[20:21], s[2:3], v41, s10, v[32:33]
	v_lshl_add_u64 v[20:21], v[20:21], 0, v[0:1]
	v_add_u32_e32 v42, 0x280, v19
	v_add_co_u32_e32 v20, vcc, s14, v20
	v_mad_i64_i32 v[22:23], s[2:3], v42, s10, v[32:33]
	s_nop 0
	v_addc_co_u32_e32 v21, vcc, 0, v21, vcc
	v_lshl_add_u64 v[22:23], v[22:23], 0, v[0:1]
	v_add_co_u32_e32 v24, vcc, s14, v22
	v_add_u32_e32 v43, 0x300, v19
	s_nop 0
	v_addc_co_u32_e32 v25, vcc, 0, v23, vcc
	global_load_dwordx4 v[20:23], v[20:21], off
	s_nop 0
	global_load_dwordx4 v[24:27], v[24:25], off
	v_mad_i64_i32 v[28:29], s[2:3], v43, s10, v[32:33]
	v_lshl_add_u64 v[28:29], v[28:29], 0, v[0:1]
	v_add_co_u32_e32 v28, vcc, s14, v28
	v_add_u32_e32 v44, 0x380, v19
	s_nop 0
	v_addc_co_u32_e32 v29, vcc, 0, v29, vcc
	global_load_dwordx4 v[28:31], v[28:29], off
	v_mad_i64_i32 v[32:33], s[2:3], v44, s10, v[32:33]
	v_lshl_add_u64 v[32:33], v[32:33], 0, v[0:1]
	v_add_co_u32_e32 v32, vcc, s14, v32
	v_lshlrev_b32_e32 v36, 8, v19
	s_nop 0
	v_addc_co_u32_e32 v33, vcc, 0, v33, vcc
	global_load_dwordx4 v[32:35], v[32:33], off
	v_and_b32_e32 v46, 0x300, v36
	v_lshrrev_b32_e32 v36, 4, v18
	v_and_b32_e32 v36, 0xfffffc0, v36
	v_add_u32_e32 v36, v46, v36
	v_bfe_u32 v19, v19, 2, 6
	v_add_u32_e32 v0, 0, v0
	v_or_b32_e32 v36, v36, v19
	s_movk_i32 s0, 0x50
	v_mad_u64_u32 v[36:37], s[2:3], v36, s0, v[0:1]
	v_ashrrev_i32_e32 v45, 6, v18
	s_mov_b32 s15, 0x8000
	s_movk_i32 s6, 0x50
	s_waitcnt vmcnt(7)
	ds_write_b128 v36, v[2:5] offset:40960
	v_lshrrev_b32_e32 v2, 2, v38
	v_and_b32_e32 v3, 0xfffffc0, v2
	v_add_u32_e32 v3, v3, v46
	v_and_or_b32 v2, v2, 63, v3
	v_mad_u64_u32 v[2:3], s[2:3], v2, s0, v[0:1]
	s_waitcnt vmcnt(6)
	ds_write_b128 v2, v[6:9] offset:40960
	v_lshrrev_b32_e32 v2, 2, v39
	v_and_b32_e32 v2, 0xfffffc0, v2
	v_add_u32_e32 v2, v2, v46
	v_or_b32_e32 v2, v2, v19
	v_mad_u64_u32 v[2:3], s[2:3], v2, s0, v[0:1]
	s_waitcnt vmcnt(5)
	ds_write_b128 v2, v[10:13] offset:40960
	v_lshrrev_b32_e32 v2, 2, v40
	v_and_b32_e32 v3, 0xfffffc0, v2
	v_add_u32_e32 v3, v3, v46
	v_and_or_b32 v2, v2, 63, v3
	v_mad_u64_u32 v[2:3], s[2:3], v2, s0, v[0:1]
	s_waitcnt vmcnt(4)
	ds_write_b128 v2, v[14:17] offset:40960
	v_lshrrev_b32_e32 v2, 2, v41
	v_and_b32_e32 v2, 0xfffffc0, v2
	v_add_u32_e32 v2, v2, v46
	v_or_b32_e32 v2, v2, v19
	v_mad_u64_u32 v[2:3], s[2:3], v2, s0, v[0:1]
	s_waitcnt vmcnt(3)
	ds_write_b128 v2, v[20:23] offset:40960
	v_lshrrev_b32_e32 v2, 2, v42
	v_and_b32_e32 v3, 0xfffffc0, v2
	v_add_u32_e32 v3, v3, v46
	v_and_or_b32 v2, v2, 63, v3
	v_mad_u64_u32 v[2:3], s[2:3], v2, s0, v[0:1]
	s_waitcnt vmcnt(2)
	ds_write_b128 v2, v[24:27] offset:40960
	v_lshrrev_b32_e32 v2, 2, v43
	v_and_b32_e32 v2, 0xfffffc0, v2
	v_add_u32_e32 v2, v2, v46
	v_or_b32_e32 v2, v2, v19
	v_mad_u64_u32 v[2:3], s[2:3], v2, s0, v[0:1]
	s_waitcnt vmcnt(1)
	ds_write_b128 v2, v[28:31] offset:40960
	v_lshrrev_b32_e32 v2, 2, v44
	v_and_b32_e32 v3, 0xfffffc0, v2
	v_add_u32_e32 v3, v3, v46
	v_and_or_b32 v2, v2, 63, v3
	v_mad_u64_u32 v[2:3], s[2:3], v2, s0, v[0:1]
	v_readlane_b32 s0, v255, 19
	s_waitcnt vmcnt(0)
	ds_write_b128 v2, v[32:35] offset:40960
	s_waitcnt lgkmcnt(0)
	v_lshl_add_u32 v88, s0, 3, v45
	v_cmp_gt_i32_e32 vcc, s15, v88
	s_barrier
; __device__ void phase0(const Params& P, LAS unsigned char* lds, const int G, const int bid) {
;     ...
;       const float* nw = P.in[4]; const float* gb = P.in[8];
;       f32x4 w4[4];
; #pragma unroll
;       for (int i = 0; i < 4; ++i) w4[i] = *(const f32x4*)(nw + 4 * lane + 256 * i);
;       const int gcol = ((lane >> 5) & 1) * 8 + ((lane >> 4) & 1) * 4 + ((lane >> 3) & 1) * 2 + ((lane >> 2) & 1);
;       const float gbias = gb[gcol];
;       for (int row0 = bid * 8 + wid; row0 < NTOK; row0 += G * 8 * 4) {
	s_and_saveexec_b64 s[2:3], vcc
	s_movk_i32 s16, 0x7fff
	s_cbranch_execz .LBB0_1064
	v_and_b32_e32 v19, 63, v18
	v_readlane_b32 s40, v254, 34
	v_lshlrev_b32_e32 v0, 4, v19
	v_readlane_b32 s41, v254, 35
	v_readlane_b32 s42, v254, 36
	v_readlane_b32 s43, v254, 37
	v_readlane_b32 s44, v254, 38
	v_readlane_b32 s45, v254, 39
	v_readlane_b32 s46, v254, 40
	v_readlane_b32 s47, v254, 41
	v_readlane_b32 s48, v254, 42
	v_readlane_b32 s49, v254, 43
	v_readlane_b32 s50, v254, 44
	v_readlane_b32 s51, v254, 45
	v_readlane_b32 s52, v254, 46
	v_readlane_b32 s53, v254, 47
	v_readlane_b32 s54, v254, 48
	v_readlane_b32 s55, v254, 49
	global_load_dwordx4 v[2:5], v0, s[48:49]
	global_load_dwordx4 v[6:9], v0, s[48:49] offset:1024
	global_load_dwordx4 v[10:13], v0, s[48:49] offset:2048
	global_load_dwordx4 v[14:17], v0, s[48:49] offset:3072
	v_readlane_b32 s40, v254, 50
	v_and_b32_e32 v0, 60, v18
	v_readlane_b32 s41, v254, 51
	v_lshl_add_u64 v[22:23], s[20:21], 0, v[0:1]
	v_readlane_b32 s42, v254, 52
	v_readlane_b32 s43, v254, 53
	v_readlane_b32 s44, v254, 54
	v_readlane_b32 s45, v254, 55
	global_load_dword v91, v0, s[40:41]
	v_lshlrev_b32_e32 v0, 3, v19
	v_lshl_add_u64 v[80:81], s[20:21], 0, v[0:1]
	v_and_b32_e32 v0, 32, v18
	v_cmp_eq_u32_e32 vcc, 0, v0
	v_cmp_ne_u32_e64 s[40:41], 0, v0
	v_and_b32_e32 v0, 16, v18
	v_cmp_eq_u32_e64 s[42:43], 0, v0
	v_and_b32_e32 v0, 8, v18
	v_readlane_b32 s46, v254, 56
	v_readlane_b32 s47, v254, 57
	v_cmp_eq_u32_e64 s[44:45], 0, v0
	v_and_b32_e32 v0, 4, v18
	v_readlane_b32 s48, v254, 58
	v_readlane_b32 s49, v254, 59
	v_cmp_eq_u32_e64 s[46:47], 0, v0
	v_and_b32_e32 v0, 3, v18
	v_cmp_eq_u32_e64 s[48:49], 0, v0
	v_and_b32_e32 v0, 64, v203
	v_readlane_b32 s50, v254, 60
	v_readlane_b32 s51, v254, 61
	v_add_u32_e32 v0, 64, v0
	v_xor_b32_e32 v18, 32, v203
	v_cmp_lt_i32_e64 s[50:51], v18, v0
	v_lshlrev_b32_e32 v20, 2, v19
	s_mov_b64 s[4:5], 0x4000000
	v_cndmask_b32_e64 v18, v203, v18, s[50:51]
	v_lshlrev_b32_e32 v96, 2, v18
	v_xor_b32_e32 v18, 16, v203
	v_cmp_lt_i32_e64 s[50:51], v18, v0
	v_mad_u32_u24 v102, v19, s6, 0
	s_lshl_b32 s0, s89, 3
	v_cndmask_b32_e64 v18, v203, v18, s[50:51]
	v_lshlrev_b32_e32 v97, 2, v18
	v_xor_b32_e32 v18, 8, v203
	v_cmp_lt_i32_e64 s[50:51], v18, v0
	v_lshl_add_u64 v[78:79], v[22:23], 0, s[4:5]
	v_add_u32_e32 v103, 0xa000, v102
	v_cndmask_b32_e64 v18, v203, v18, s[50:51]
	v_lshlrev_b32_e32 v98, 2, v18
	v_xor_b32_e32 v18, 4, v203
	v_cmp_lt_i32_e64 s[50:51], v18, v0
	v_add_u32_e32 v104, 0x1a400, v102
	v_add_u32_e32 v105, 0x1a410, v102
	v_cndmask_b32_e64 v18, v203, v18, s[50:51]
	v_lshlrev_b32_e32 v99, 2, v18
	v_xor_b32_e32 v18, 2, v203
	v_cmp_lt_i32_e64 s[50:51], v18, v0
	v_add_u32_e32 v106, 0x1a420, v102
	v_add_u32_e32 v107, 0x1a430, v102
	v_cndmask_b32_e64 v18, v203, v18, s[50:51]
	v_lshlrev_b32_e32 v100, 2, v18
	v_xor_b32_e32 v18, 1, v203
	v_cmp_lt_i32_e64 s[50:51], v18, v0
	v_add_u32_e32 v108, 0x1b800, v102
	v_add_u32_e32 v109, 0x1b810, v102
	v_cndmask_b32_e64 v0, v203, v18, s[50:51]
	v_lshlrev_b32_e32 v101, 2, v0
	v_add_u32_e32 v110, 0x1b820, v102
	v_add_u32_e32 v111, 0x1b830, v102
	v_add_u32_e32 v112, 0x1cc00, v102
	v_add_u32_e32 v113, 0x1cc10, v102
	v_add_u32_e32 v114, 0x1cc20, v102
	v_add_u32_e32 v115, 0x1cc30, v102
	s_lshl_b32 s10, s89, 4
	s_mul_i32 s11, s89, 24
	s_mov_b64 s[4:5], 0
	v_lshlrev_b32_e32 v0, 2, v20
	v_readlane_b32 s52, v254, 62
	v_readlane_b32 s53, v254, 63
	v_readlane_b32 s54, v255, 0
	v_readlane_b32 s55, v255, 1
	s_branch .LBB0_1046
